# v25 + accumulator zeroing between units with v_pk_mov_b32 pairs (64 instead of 128 VALU per unit)
# speedup vs baseline: 1.0030x; 1.0030x over previous
; template <class Epi, class Sched>
; __device__ __forceinline__ void gemm_phase(LAS unsigned char* lds, const Gemm g, Sched S, const Epi& E) {
;     ...
; #pragma unroll
;         for (int a = 0; a < 2; ++a)
; #pragma unroll
;             for (int b = 0; b < 2; ++b)
; #pragma unroll
;                 for (int m = 0; m < 4; ++m)
; #pragma unroll
;                     for (int n = 0; n < 2; ++n) acc[a][b][m][n] = (f32x4){0.f, 0.f, 0.f, 0.f};
;         cur = nxt; cA = nA; cB = nB; ++ui;
.LBB0_629:
	s_add_u32 s63, s0, 0x100
	s_addc_u32 s64, s1, 0
	s_add_u32 s0, s76, 0x40080
	v_mov_b32_e32 v2, 0
	v_mov_b32_e32 v3, 0
	v_pk_mov_b32 v[4:5], v[2:3], v[2:3]
	v_pk_mov_b32 v[6:7], v[2:3], v[2:3]
	v_pk_mov_b32 v[8:9], v[2:3], v[2:3]
	v_pk_mov_b32 v[10:11], v[2:3], v[2:3]
	v_pk_mov_b32 v[12:13], v[2:3], v[2:3]
	v_pk_mov_b32 v[14:15], v[2:3], v[2:3]
	v_pk_mov_b32 v[16:17], v[2:3], v[2:3]
	v_pk_mov_b32 v[18:19], v[2:3], v[2:3]
	v_pk_mov_b32 v[20:21], v[2:3], v[2:3]
	v_pk_mov_b32 v[22:23], v[2:3], v[2:3]
	v_pk_mov_b32 v[24:25], v[2:3], v[2:3]
	v_pk_mov_b32 v[26:27], v[2:3], v[2:3]
	v_pk_mov_b32 v[28:29], v[2:3], v[2:3]
	v_pk_mov_b32 v[30:31], v[2:3], v[2:3]
	v_pk_mov_b32 v[32:33], v[2:3], v[2:3]
	v_pk_mov_b32 v[34:35], v[2:3], v[2:3]
	v_pk_mov_b32 v[36:37], v[2:3], v[2:3]
	v_pk_mov_b32 v[38:39], v[2:3], v[2:3]
	v_pk_mov_b32 v[40:41], v[2:3], v[2:3]
	v_pk_mov_b32 v[42:43], v[2:3], v[2:3]
	v_pk_mov_b32 v[44:45], v[2:3], v[2:3]
	v_pk_mov_b32 v[46:47], v[2:3], v[2:3]
	v_pk_mov_b32 v[48:49], v[2:3], v[2:3]
	v_pk_mov_b32 v[50:51], v[2:3], v[2:3]
	v_pk_mov_b32 v[52:53], v[2:3], v[2:3]
	v_pk_mov_b32 v[54:55], v[2:3], v[2:3]
	v_pk_mov_b32 v[56:57], v[2:3], v[2:3]
	v_pk_mov_b32 v[58:59], v[2:3], v[2:3]
	v_pk_mov_b32 v[60:61], v[2:3], v[2:3]
	v_pk_mov_b32 v[62:63], v[2:3], v[2:3]
	v_pk_mov_b32 v[64:65], v[2:3], v[2:3]
	v_pk_mov_b32 v[66:67], v[2:3], v[2:3]
	v_pk_mov_b32 v[68:69], v[2:3], v[2:3]
	v_pk_mov_b32 v[70:71], v[2:3], v[2:3]
	v_pk_mov_b32 v[72:73], v[2:3], v[2:3]
	v_pk_mov_b32 v[74:75], v[2:3], v[2:3]
	v_pk_mov_b32 v[76:77], v[2:3], v[2:3]
	v_pk_mov_b32 v[78:79], v[2:3], v[2:3]
	v_pk_mov_b32 v[80:81], v[2:3], v[2:3]
	v_pk_mov_b32 v[82:83], v[2:3], v[2:3]
	v_pk_mov_b32 v[84:85], v[2:3], v[2:3]
	v_pk_mov_b32 v[86:87], v[2:3], v[2:3]
	v_pk_mov_b32 v[88:89], v[2:3], v[2:3]
	v_pk_mov_b32 v[90:91], v[2:3], v[2:3]
	v_pk_mov_b32 v[92:93], v[2:3], v[2:3]
	v_pk_mov_b32 v[94:95], v[2:3], v[2:3]
	v_pk_mov_b32 v[96:97], v[2:3], v[2:3]
	v_pk_mov_b32 v[98:99], v[2:3], v[2:3]
	v_pk_mov_b32 v[100:101], v[2:3], v[2:3]
	v_pk_mov_b32 v[102:103], v[2:3], v[2:3]
	v_pk_mov_b32 v[104:105], v[2:3], v[2:3]
	v_pk_mov_b32 v[106:107], v[2:3], v[2:3]
	v_pk_mov_b32 v[108:109], v[2:3], v[2:3]
	v_pk_mov_b32 v[110:111], v[2:3], v[2:3]
	v_pk_mov_b32 v[112:113], v[2:3], v[2:3]
	v_pk_mov_b32 v[114:115], v[2:3], v[2:3]
	v_pk_mov_b32 v[116:117], v[2:3], v[2:3]
	v_pk_mov_b32 v[118:119], v[2:3], v[2:3]
	v_pk_mov_b32 v[120:121], v[2:3], v[2:3]
	v_pk_mov_b32 v[122:123], v[2:3], v[2:3]
	v_pk_mov_b32 v[124:125], v[2:3], v[2:3]
	v_pk_mov_b32 v[126:127], v[2:3], v[2:3]
	v_pk_mov_b32 v[128:129], v[2:3], v[2:3]
	s_addc_u32 s1, s77, 0
	s_mov_b32 s65, 0

; template <class Epi, class Sched>
; __device__ __forceinline__ void gemm_phase(LAS unsigned char* lds, const Gemm g, Sched S, const Epi& E) {
;     ...
; #pragma unroll
;         for (int a = 0; a < 2; ++a)
; #pragma unroll
;             for (int b = 0; b < 2; ++b)
; #pragma unroll
;                 for (int m = 0; m < 4; ++m)
; #pragma unroll
;                     for (int n = 0; n < 2; ++n) acc[a][b][m][n] = (f32x4){0.f, 0.f, 0.f, 0.f};
;         cur = nxt; cA = nA; cB = nB; ++ui;
.LBB0_726:
	s_add_u32 s11, s44, 0x100
	s_addc_u32 s19, s45, 0
	s_add_u32 s42, s42, 0x80
	v_mov_b32_e32 v2, 0
	v_mov_b32_e32 v3, 0
	v_pk_mov_b32 v[4:5], v[2:3], v[2:3]
	v_pk_mov_b32 v[6:7], v[2:3], v[2:3]
	v_pk_mov_b32 v[8:9], v[2:3], v[2:3]
	v_pk_mov_b32 v[10:11], v[2:3], v[2:3]
	v_pk_mov_b32 v[12:13], v[2:3], v[2:3]
	v_pk_mov_b32 v[14:15], v[2:3], v[2:3]
	v_pk_mov_b32 v[16:17], v[2:3], v[2:3]
	v_pk_mov_b32 v[18:19], v[2:3], v[2:3]
	v_pk_mov_b32 v[20:21], v[2:3], v[2:3]
	v_pk_mov_b32 v[22:23], v[2:3], v[2:3]
	v_pk_mov_b32 v[24:25], v[2:3], v[2:3]
	v_pk_mov_b32 v[26:27], v[2:3], v[2:3]
	v_pk_mov_b32 v[28:29], v[2:3], v[2:3]
	v_pk_mov_b32 v[30:31], v[2:3], v[2:3]
	v_pk_mov_b32 v[32:33], v[2:3], v[2:3]
	v_pk_mov_b32 v[34:35], v[2:3], v[2:3]
	v_pk_mov_b32 v[36:37], v[2:3], v[2:3]
	v_pk_mov_b32 v[38:39], v[2:3], v[2:3]
	v_pk_mov_b32 v[40:41], v[2:3], v[2:3]
	v_pk_mov_b32 v[42:43], v[2:3], v[2:3]
	v_pk_mov_b32 v[44:45], v[2:3], v[2:3]
	v_pk_mov_b32 v[46:47], v[2:3], v[2:3]
	v_pk_mov_b32 v[48:49], v[2:3], v[2:3]
	v_pk_mov_b32 v[50:51], v[2:3], v[2:3]
	v_pk_mov_b32 v[52:53], v[2:3], v[2:3]
	v_pk_mov_b32 v[54:55], v[2:3], v[2:3]
	v_pk_mov_b32 v[56:57], v[2:3], v[2:3]
	v_pk_mov_b32 v[58:59], v[2:3], v[2:3]
	v_pk_mov_b32 v[60:61], v[2:3], v[2:3]
	v_pk_mov_b32 v[62:63], v[2:3], v[2:3]
	v_pk_mov_b32 v[64:65], v[2:3], v[2:3]
	v_pk_mov_b32 v[66:67], v[2:3], v[2:3]
	v_pk_mov_b32 v[68:69], v[2:3], v[2:3]
	v_pk_mov_b32 v[70:71], v[2:3], v[2:3]
	v_pk_mov_b32 v[72:73], v[2:3], v[2:3]
	v_pk_mov_b32 v[74:75], v[2:3], v[2:3]
	v_pk_mov_b32 v[76:77], v[2:3], v[2:3]
	v_pk_mov_b32 v[78:79], v[2:3], v[2:3]
	v_pk_mov_b32 v[80:81], v[2:3], v[2:3]
	v_pk_mov_b32 v[82:83], v[2:3], v[2:3]
	v_pk_mov_b32 v[84:85], v[2:3], v[2:3]
	v_pk_mov_b32 v[86:87], v[2:3], v[2:3]
	v_pk_mov_b32 v[88:89], v[2:3], v[2:3]
	v_pk_mov_b32 v[90:91], v[2:3], v[2:3]
	v_pk_mov_b32 v[92:93], v[2:3], v[2:3]
	v_pk_mov_b32 v[94:95], v[2:3], v[2:3]
	v_pk_mov_b32 v[96:97], v[2:3], v[2:3]
	v_pk_mov_b32 v[98:99], v[2:3], v[2:3]
	v_pk_mov_b32 v[100:101], v[2:3], v[2:3]
	v_pk_mov_b32 v[102:103], v[2:3], v[2:3]
	v_pk_mov_b32 v[104:105], v[2:3], v[2:3]
	v_pk_mov_b32 v[106:107], v[2:3], v[2:3]
	v_pk_mov_b32 v[108:109], v[2:3], v[2:3]
	v_pk_mov_b32 v[110:111], v[2:3], v[2:3]
	v_pk_mov_b32 v[112:113], v[2:3], v[2:3]
	v_pk_mov_b32 v[138:139], v[2:3], v[2:3]
	v_pk_mov_b32 v[140:141], v[2:3], v[2:3]
	v_pk_mov_b32 v[142:143], v[2:3], v[2:3]
	v_pk_mov_b32 v[144:145], v[2:3], v[2:3]
	v_pk_mov_b32 v[146:147], v[2:3], v[2:3]
	v_pk_mov_b32 v[148:149], v[2:3], v[2:3]
	v_pk_mov_b32 v[150:151], v[2:3], v[2:3]
	v_pk_mov_b32 v[152:153], v[2:3], v[2:3]
	s_addc_u32 s43, s43, 0
	s_mov_b32 s20, 0
	s_waitcnt lgkmcnt(0)

; template <class Epi, class Sched>
; __device__ __forceinline__ void gemm_phase(LAS unsigned char* lds, const Gemm g, Sched S, const Epi& E) {
;     ...
;         const bool has_next = S.next(ui + 1, nxt);
;         const char* nA = has_next ? (const char*)g.A + a_off(g, nxt) : cA; const char* nB = has_next ? (const char*)g.Bt + b_off(g, nxt) : cB;
;     ...
; #pragma unroll
;         for (int a = 0; a < 2; ++a)
; #pragma unroll
;             for (int b = 0; b < 2; ++b)
; #pragma unroll
;                 for (int m = 0; m < 4; ++m)
; #pragma unroll
;                     for (int n = 0; n < 2; ++n) acc[a][b][m][n] = (f32x4){0.f, 0.f, 0.f, 0.f};
;         cur = nxt; cA = nA; cB = nB; ++ui;
.LBB0_769:
	s_add_i32 s77, s77, s41
	s_cmp_lt_i32 s77, s2
	s_cselect_b64 s[90:91], -1, 0
	s_cmp_ge_i32 s77, s2
	s_cselect_b64 s[0:1], -1, 0
	s_lshl_b32 s3, s85, 3
	s_and_b32 s34, s92, 7
	s_or_b32 s93, s34, s3
	s_ashr_i32 s94, s92, 3
	s_and_b64 s[34:35], s[90:91], exec
	s_cselect_b32 s34, s93, s44
	s_cselect_b32 s44, s94, s45
	s_ashr_i32 s35, s34, 31
	s_lshl_b64 s[34:35], s[34:35], 19
	s_add_u32 s34, s14, s34
	s_addc_u32 s35, s15, s35
	s_and_b64 s[60:61], s[90:91], exec
	s_cselect_b32 s60, s35, s11
	s_cselect_b32 s61, s34, s10
	s_ashr_i32 s45, s44, 31
	s_lshl_b64 s[44:45], s[44:45], 19
	s_add_u32 s88, s40, s44
	s_addc_u32 s89, s66, s45
	s_and_b64 s[44:45], s[90:91], exec
	s_cselect_b32 s62, s89, s43
	s_cselect_b32 s63, s88, s42
	s_add_u32 s64, s42, 0x100
	s_addc_u32 s65, s43, 0
	s_add_u32 s10, s10, 0x40080
	v_mov_b32_e32 v2, 0
	v_mov_b32_e32 v3, 0
	v_pk_mov_b32 v[4:5], v[2:3], v[2:3]
	v_pk_mov_b32 v[6:7], v[2:3], v[2:3]
	v_pk_mov_b32 v[8:9], v[2:3], v[2:3]
	v_pk_mov_b32 v[10:11], v[2:3], v[2:3]
	v_pk_mov_b32 v[12:13], v[2:3], v[2:3]
	v_pk_mov_b32 v[14:15], v[2:3], v[2:3]
	v_pk_mov_b32 v[16:17], v[2:3], v[2:3]
	v_pk_mov_b32 v[18:19], v[2:3], v[2:3]
	v_pk_mov_b32 v[20:21], v[2:3], v[2:3]
	v_pk_mov_b32 v[22:23], v[2:3], v[2:3]
	v_pk_mov_b32 v[24:25], v[2:3], v[2:3]
	v_pk_mov_b32 v[26:27], v[2:3], v[2:3]
	v_pk_mov_b32 v[28:29], v[2:3], v[2:3]
	v_pk_mov_b32 v[30:31], v[2:3], v[2:3]
	v_pk_mov_b32 v[32:33], v[2:3], v[2:3]
	v_pk_mov_b32 v[34:35], v[2:3], v[2:3]
	v_pk_mov_b32 v[36:37], v[2:3], v[2:3]
	v_pk_mov_b32 v[38:39], v[2:3], v[2:3]
	v_pk_mov_b32 v[40:41], v[2:3], v[2:3]
	v_pk_mov_b32 v[42:43], v[2:3], v[2:3]
	v_pk_mov_b32 v[44:45], v[2:3], v[2:3]
	v_pk_mov_b32 v[46:47], v[2:3], v[2:3]
	v_pk_mov_b32 v[48:49], v[2:3], v[2:3]
	v_pk_mov_b32 v[50:51], v[2:3], v[2:3]
	v_pk_mov_b32 v[52:53], v[2:3], v[2:3]
	v_pk_mov_b32 v[54:55], v[2:3], v[2:3]
	v_pk_mov_b32 v[56:57], v[2:3], v[2:3]
	v_pk_mov_b32 v[58:59], v[2:3], v[2:3]
	v_pk_mov_b32 v[60:61], v[2:3], v[2:3]
	v_pk_mov_b32 v[62:63], v[2:3], v[2:3]
	v_pk_mov_b32 v[64:65], v[2:3], v[2:3]
	v_pk_mov_b32 v[66:67], v[2:3], v[2:3]
	v_pk_mov_b32 v[68:69], v[2:3], v[2:3]
	v_pk_mov_b32 v[70:71], v[2:3], v[2:3]
	v_pk_mov_b32 v[72:73], v[2:3], v[2:3]
	v_pk_mov_b32 v[74:75], v[2:3], v[2:3]
	v_pk_mov_b32 v[76:77], v[2:3], v[2:3]
	v_pk_mov_b32 v[78:79], v[2:3], v[2:3]
	v_pk_mov_b32 v[80:81], v[2:3], v[2:3]
	v_pk_mov_b32 v[82:83], v[2:3], v[2:3]
	v_pk_mov_b32 v[84:85], v[2:3], v[2:3]
	v_pk_mov_b32 v[86:87], v[2:3], v[2:3]
	v_pk_mov_b32 v[88:89], v[2:3], v[2:3]
	v_pk_mov_b32 v[90:91], v[2:3], v[2:3]
	v_pk_mov_b32 v[92:93], v[2:3], v[2:3]
	v_pk_mov_b32 v[94:95], v[2:3], v[2:3]
	v_pk_mov_b32 v[96:97], v[2:3], v[2:3]
	v_pk_mov_b32 v[98:99], v[2:3], v[2:3]
	v_pk_mov_b32 v[100:101], v[2:3], v[2:3]
	v_pk_mov_b32 v[102:103], v[2:3], v[2:3]
	v_pk_mov_b32 v[104:105], v[2:3], v[2:3]
	v_pk_mov_b32 v[106:107], v[2:3], v[2:3]
	v_pk_mov_b32 v[108:109], v[2:3], v[2:3]
	v_pk_mov_b32 v[110:111], v[2:3], v[2:3]
	v_pk_mov_b32 v[112:113], v[2:3], v[2:3]
	v_pk_mov_b32 v[114:115], v[2:3], v[2:3]
	v_pk_mov_b32 v[116:117], v[2:3], v[2:3]
	v_pk_mov_b32 v[118:119], v[2:3], v[2:3]
	v_pk_mov_b32 v[120:121], v[2:3], v[2:3]
	v_pk_mov_b32 v[122:123], v[2:3], v[2:3]
	v_pk_mov_b32 v[124:125], v[2:3], v[2:3]
	v_pk_mov_b32 v[126:127], v[2:3], v[2:3]
	v_pk_mov_b32 v[128:129], v[2:3], v[2:3]
	s_addc_u32 s11, s11, 0
	s_mov_b32 s70, -2
